# GLU/SWIGLU GEMM epilogue: IEEE f32 division expansion replaced by v_rcp_f32 + v_mul_f32 (f32 kept)
# speedup vs baseline: 1.0240x; 1.0240x over previous
.LBB0_1044:
	s_waitcnt vmcnt(0)
	v_pk_add_f32 v[128:129], v[128:129], v[144:145]
	v_pk_add_f32 v[126:127], v[126:127], v[142:143]
	v_pk_add_f32 v[162:163], v[124:125], v[140:141]
	v_pk_add_f32 v[164:165], v[122:123], v[138:139]
	s_mov_b64 s[6:7], -1
	s_and_b64 vcc, exec, s[2:3]
	s_cbranch_vccz .LBB0_1046
	v_mul_f32_e32 v122, 0xbfb8aa3b, v126
	v_mul_f32_e32 v123, 0xbfb8aa3b, v127
	v_exp_f32_e32 v122, v122
	v_exp_f32_e32 v123, v123
	v_mul_f32_e32 v124, 0xbfb8aa3b, v128
	v_mul_f32_e32 v125, 0xbfb8aa3b, v129
	v_exp_f32_e32 v124, v124
	v_pk_add_f32 v[122:123], v[122:123], 1.0 op_sel_hi:[1,0]
	v_exp_f32_e32 v125, v125
	v_rcp_f32_e32 v166, v123
	v_pk_add_f32 v[124:125], v[124:125], 1.0 op_sel_hi:[1,0]
	s_mov_b64 s[6:7], 0
	v_mul_f32_e32 v123, v127, v166
	v_rcp_f32_e32 v166, v122
	s_nop 0
	v_mul_f32_e32 v122, v126, v166
	v_rcp_f32_e32 v166, v125
	v_pk_mul_f32 v[122:123], v[164:165], v[122:123]
	v_mul_f32_e32 v125, v129, v166
	v_rcp_f32_e32 v166, v124
	s_nop 0
	v_mul_f32_e32 v124, v128, v166
	v_pk_mul_f32 v[124:125], v[162:163], v[124:125]
.LBB0_1046:
	s_andn2_b64 vcc, exec, s[6:7]
	s_cbranch_vccnz .LBB0_1048
	v_mul_f32_e32 v122, 0xbfb8aa3b, v164
	v_mul_f32_e32 v123, 0xbfb8aa3b, v165
	v_exp_f32_e32 v122, v122
	v_exp_f32_e32 v123, v123
	v_mul_f32_e32 v124, 0xbfb8aa3b, v162
	v_mul_f32_e32 v125, 0xbfb8aa3b, v163
	v_exp_f32_e32 v124, v124
	v_pk_add_f32 v[122:123], v[122:123], 1.0 op_sel_hi:[1,0]
	v_exp_f32_e32 v125, v125
	v_rcp_f32_e32 v162, v123
	v_pk_add_f32 v[124:125], v[124:125], 1.0 op_sel_hi:[1,0]
	v_mov_b32_e32 v123, v162
	v_rcp_f32_e32 v162, v122
	s_nop 0
	v_mov_b32_e32 v122, v162
	v_rcp_f32_e32 v162, v125
	v_pk_mul_f32 v[122:123], v[126:127], v[122:123]
	v_mov_b32_e32 v125, v162
	v_rcp_f32_e32 v162, v124
	s_nop 0
	v_mov_b32_e32 v124, v162
	v_pk_mul_f32 v[124:125], v[128:129], v[124:125]
.LBB0_1048:
	v_lshl_add_u64 v[126:127], v[146:147], 1, v[148:149]
	v_mad_i64_i32 v[128:129], s[2:3], v0, v160, 0
	v_lshl_add_u64 v[128:129], v[128:129], 1, v[126:127]
	v_cvt_pk_bf16_f32 v122, v122, v123
	v_cvt_pk_bf16_f32 v123, v124, v125
	global_store_dwordx2 v[128:129], v[122:123], off
	v_pk_add_f32 v[120:121], v[120:121], v[132:133]
	v_pk_add_f32 v[118:119], v[118:119], v[130:131]
	v_pk_add_f32 v[122:123], v[116:117], v[136:137]
	v_pk_add_f32 v[124:125], v[114:115], v[134:135]
	s_and_b64 vcc, exec, s[4:5]
	s_mov_b64 s[2:3], -1
	s_cbranch_vccnz .LBB0_1050
	v_mul_f32_e32 v114, 0xbfb8aa3b, v118
	v_mul_f32_e32 v115, 0xbfb8aa3b, v119
	v_exp_f32_e32 v114, v114
	v_exp_f32_e32 v115, v115
	v_mul_f32_e32 v116, 0xbfb8aa3b, v120
	v_mul_f32_e32 v117, 0xbfb8aa3b, v121
	v_exp_f32_e32 v116, v116
	v_pk_add_f32 v[114:115], v[114:115], 1.0 op_sel_hi:[1,0]
	v_exp_f32_e32 v117, v117
	v_rcp_f32_e32 v147, v115
	v_pk_add_f32 v[116:117], v[116:117], 1.0 op_sel_hi:[1,0]
	v_mul_f32_e32 v115, v119, v147
	v_rcp_f32_e32 v147, v114
	s_nop 0
	v_mul_f32_e32 v114, v118, v147
	v_rcp_f32_e32 v147, v117
	v_pk_mul_f32 v[114:115], v[124:125], v[114:115]
	v_mul_f32_e32 v117, v121, v147
	v_rcp_f32_e32 v147, v116
	s_mov_b64 s[2:3], 0
	v_mul_f32_e32 v116, v120, v147
	v_pk_mul_f32 v[116:117], v[122:123], v[116:117]
.LBB0_1050:
	s_andn2_b64 vcc, exec, s[2:3]
	s_cbranch_vccnz .LBB0_1052
	v_mul_f32_e32 v114, 0xbfb8aa3b, v124
	v_mul_f32_e32 v115, 0xbfb8aa3b, v125
	v_exp_f32_e32 v114, v114
	v_exp_f32_e32 v115, v115
	v_mul_f32_e32 v116, 0xbfb8aa3b, v122
	v_mul_f32_e32 v117, 0xbfb8aa3b, v123
	v_exp_f32_e32 v116, v116
	v_pk_add_f32 v[114:115], v[114:115], 1.0 op_sel_hi:[1,0]
	v_exp_f32_e32 v117, v117
	v_rcp_f32_e32 v123, v115
	v_pk_add_f32 v[116:117], v[116:117], 1.0 op_sel_hi:[1,0]
	v_mov_b32_e32 v115, v123
	v_rcp_f32_e32 v123, v114
	s_nop 0
	v_mov_b32_e32 v114, v123
	v_rcp_f32_e32 v123, v117
	v_pk_mul_f32 v[114:115], v[118:119], v[114:115]
	v_mov_b32_e32 v117, v123
	v_rcp_f32_e32 v123, v116
	s_nop 0
	v_mov_b32_e32 v116, v123
	v_pk_mul_f32 v[116:117], v[120:121], v[116:117]
.LBB0_1052:
	v_cvt_pk_bf16_f32 v114, v114, v115
	v_cvt_pk_bf16_f32 v115, v116, v117
	global_store_dwordx2 v[128:129], v[114:115], off offset:32
	v_pk_add_f32 v[112:113], v[112:113], v[144:145]
	v_pk_add_f32 v[110:111], v[110:111], v[142:143]
	v_pk_add_f32 v[114:115], v[108:109], v[140:141]
	v_pk_add_f32 v[116:117], v[106:107], v[138:139]
	s_and_b64 vcc, exec, s[4:5]
	s_mov_b64 s[2:3], -1
	s_cbranch_vccnz .LBB0_1054
	v_mul_f32_e32 v106, 0xbfb8aa3b, v110
	v_mul_f32_e32 v107, 0xbfb8aa3b, v111
	v_exp_f32_e32 v106, v106
	v_exp_f32_e32 v107, v107
	v_mul_f32_e32 v108, 0xbfb8aa3b, v112
	v_mul_f32_e32 v109, 0xbfb8aa3b, v113
	v_exp_f32_e32 v108, v108
	v_pk_add_f32 v[106:107], v[106:107], 1.0 op_sel_hi:[1,0]
	v_exp_f32_e32 v109, v109
	v_rcp_f32_e32 v119, v107
	v_pk_add_f32 v[108:109], v[108:109], 1.0 op_sel_hi:[1,0]
	v_mul_f32_e32 v107, v111, v119
	v_rcp_f32_e32 v119, v106
	s_nop 0
	v_mul_f32_e32 v106, v110, v119
	v_rcp_f32_e32 v119, v109
	v_pk_mul_f32 v[106:107], v[116:117], v[106:107]
	v_mul_f32_e32 v109, v113, v119
	v_rcp_f32_e32 v119, v108
	s_mov_b64 s[2:3], 0
	v_mul_f32_e32 v108, v112, v119
	v_pk_mul_f32 v[108:109], v[114:115], v[108:109]
.LBB0_1054:
	s_andn2_b64 vcc, exec, s[2:3]
	s_cbranch_vccnz .LBB0_1056
	v_mul_f32_e32 v106, 0xbfb8aa3b, v116
	v_mul_f32_e32 v107, 0xbfb8aa3b, v117
	v_exp_f32_e32 v106, v106
	v_exp_f32_e32 v107, v107
	v_mul_f32_e32 v108, 0xbfb8aa3b, v114
	v_mul_f32_e32 v109, 0xbfb8aa3b, v115
	v_exp_f32_e32 v108, v108
	v_pk_add_f32 v[106:107], v[106:107], 1.0 op_sel_hi:[1,0]
	v_exp_f32_e32 v109, v109
	v_rcp_f32_e32 v115, v107
	v_pk_add_f32 v[108:109], v[108:109], 1.0 op_sel_hi:[1,0]
	v_mov_b32_e32 v107, v115
	v_rcp_f32_e32 v115, v106
	s_nop 0
	v_mov_b32_e32 v106, v115
	v_rcp_f32_e32 v115, v109
	v_pk_mul_f32 v[106:107], v[110:111], v[106:107]
	v_mov_b32_e32 v109, v115
	v_rcp_f32_e32 v115, v108
	s_nop 0
	v_mov_b32_e32 v108, v115
	v_pk_mul_f32 v[108:109], v[112:113], v[108:109]
.LBB0_1056:
	v_add_u32_e32 v110, 16, v160
	v_mad_i64_i32 v[110:111], s[2:3], v0, v110, 0
	v_lshl_add_u64 v[110:111], v[110:111], 1, v[126:127]
	v_cvt_pk_bf16_f32 v106, v106, v107
	v_cvt_pk_bf16_f32 v107, v108, v109
	global_store_dwordx2 v[110:111], v[106:107], off
	v_pk_add_f32 v[104:105], v[104:105], v[132:133]
	v_pk_add_f32 v[102:103], v[102:103], v[130:131]
	v_pk_add_f32 v[106:107], v[100:101], v[136:137]
	v_pk_add_f32 v[108:109], v[98:99], v[134:135]
	s_and_b64 vcc, exec, s[4:5]
	s_mov_b64 s[2:3], -1
	s_cbranch_vccnz .LBB0_1058
	v_mul_f32_e32 v98, 0xbfb8aa3b, v102
	v_mul_f32_e32 v99, 0xbfb8aa3b, v103
	v_exp_f32_e32 v98, v98
	v_exp_f32_e32 v99, v99
	v_mul_f32_e32 v100, 0xbfb8aa3b, v104
	v_mul_f32_e32 v101, 0xbfb8aa3b, v105
	v_exp_f32_e32 v100, v100
	v_pk_add_f32 v[98:99], v[98:99], 1.0 op_sel_hi:[1,0]
	v_exp_f32_e32 v101, v101
	v_rcp_f32_e32 v113, v99
	v_pk_add_f32 v[100:101], v[100:101], 1.0 op_sel_hi:[1,0]
	v_mul_f32_e32 v99, v103, v113
	v_rcp_f32_e32 v113, v98
	s_nop 0
	v_mul_f32_e32 v98, v102, v113
	v_rcp_f32_e32 v113, v101
	v_pk_mul_f32 v[98:99], v[108:109], v[98:99]
	v_mul_f32_e32 v101, v105, v113
	v_rcp_f32_e32 v113, v100
	s_mov_b64 s[2:3], 0
	v_mul_f32_e32 v100, v104, v113
	v_pk_mul_f32 v[100:101], v[106:107], v[100:101]
.LBB0_1058:
	s_andn2_b64 vcc, exec, s[2:3]
	s_cbranch_vccnz .LBB0_1060
	v_mul_f32_e32 v98, 0xbfb8aa3b, v108
	v_mul_f32_e32 v99, 0xbfb8aa3b, v109
	v_exp_f32_e32 v98, v98
	v_exp_f32_e32 v99, v99
	v_mul_f32_e32 v100, 0xbfb8aa3b, v106
	v_mul_f32_e32 v101, 0xbfb8aa3b, v107
	v_exp_f32_e32 v100, v100
	v_pk_add_f32 v[98:99], v[98:99], 1.0 op_sel_hi:[1,0]
	v_exp_f32_e32 v101, v101
	v_rcp_f32_e32 v107, v99
	v_pk_add_f32 v[100:101], v[100:101], 1.0 op_sel_hi:[1,0]
	v_mov_b32_e32 v99, v107
	v_rcp_f32_e32 v107, v98
	s_nop 0
	v_mov_b32_e32 v98, v107
	v_rcp_f32_e32 v107, v101
	v_pk_mul_f32 v[98:99], v[102:103], v[98:99]
	v_mov_b32_e32 v101, v107
	v_rcp_f32_e32 v107, v100
	s_nop 0
	v_mov_b32_e32 v100, v107
	v_pk_mul_f32 v[100:101], v[104:105], v[100:101]
.LBB0_1060:
	v_cvt_pk_bf16_f32 v98, v98, v99
	v_cvt_pk_bf16_f32 v99, v100, v101
	global_store_dwordx2 v[110:111], v[98:99], off offset:32
	v_pk_add_f32 v[96:97], v[96:97], v[144:145]
	v_pk_add_f32 v[94:95], v[94:95], v[142:143]
	v_pk_add_f32 v[98:99], v[92:93], v[140:141]
	v_pk_add_f32 v[100:101], v[90:91], v[138:139]
	s_and_b64 vcc, exec, s[4:5]
	s_mov_b64 s[2:3], -1
	s_cbranch_vccnz .LBB0_1062
	v_mul_f32_e32 v90, 0xbfb8aa3b, v94
	v_mul_f32_e32 v91, 0xbfb8aa3b, v95
	v_exp_f32_e32 v90, v90
	v_exp_f32_e32 v91, v91
	v_mul_f32_e32 v92, 0xbfb8aa3b, v96
	v_mul_f32_e32 v93, 0xbfb8aa3b, v97
	v_exp_f32_e32 v92, v92
	v_pk_add_f32 v[90:91], v[90:91], 1.0 op_sel_hi:[1,0]
	v_exp_f32_e32 v93, v93
	v_rcp_f32_e32 v103, v91
	v_pk_add_f32 v[92:93], v[92:93], 1.0 op_sel_hi:[1,0]
	v_mul_f32_e32 v91, v95, v103
	v_rcp_f32_e32 v103, v90
	s_nop 0
	v_mul_f32_e32 v90, v94, v103
	v_rcp_f32_e32 v103, v93
	v_pk_mul_f32 v[90:91], v[100:101], v[90:91]
	v_mul_f32_e32 v93, v97, v103
	v_rcp_f32_e32 v103, v92
	s_mov_b64 s[2:3], 0
	v_mul_f32_e32 v92, v96, v103
	v_pk_mul_f32 v[92:93], v[98:99], v[92:93]
.LBB0_1062:
	s_andn2_b64 vcc, exec, s[2:3]
	s_cbranch_vccnz .LBB0_1064
	v_mul_f32_e32 v90, 0xbfb8aa3b, v100
	v_mul_f32_e32 v91, 0xbfb8aa3b, v101
	v_exp_f32_e32 v90, v90
	v_exp_f32_e32 v91, v91
	v_mul_f32_e32 v92, 0xbfb8aa3b, v98
	v_mul_f32_e32 v93, 0xbfb8aa3b, v99
	v_exp_f32_e32 v92, v92
	v_pk_add_f32 v[90:91], v[90:91], 1.0 op_sel_hi:[1,0]
	v_exp_f32_e32 v93, v93
	v_rcp_f32_e32 v99, v91
	v_pk_add_f32 v[92:93], v[92:93], 1.0 op_sel_hi:[1,0]
	v_mov_b32_e32 v91, v99
	v_rcp_f32_e32 v99, v90
	s_nop 0
	v_mov_b32_e32 v90, v99
	v_rcp_f32_e32 v99, v93
	v_pk_mul_f32 v[90:91], v[94:95], v[90:91]
	v_mov_b32_e32 v93, v99
	v_rcp_f32_e32 v99, v92
	s_nop 0
	v_mov_b32_e32 v92, v99
	v_pk_mul_f32 v[92:93], v[96:97], v[92:93]
.LBB0_1064:
	v_add_u32_e32 v94, 32, v160
	v_mad_i64_i32 v[94:95], s[2:3], v0, v94, 0
	v_lshl_add_u64 v[94:95], v[94:95], 1, v[126:127]
	v_cvt_pk_bf16_f32 v90, v90, v91
	v_cvt_pk_bf16_f32 v91, v92, v93
	global_store_dwordx2 v[94:95], v[90:91], off
	v_pk_add_f32 v[88:89], v[88:89], v[132:133]
	v_pk_add_f32 v[86:87], v[86:87], v[130:131]
	v_pk_add_f32 v[90:91], v[84:85], v[136:137]
	v_pk_add_f32 v[92:93], v[82:83], v[134:135]
	s_and_b64 vcc, exec, s[4:5]
	s_mov_b64 s[2:3], -1
	s_cbranch_vccnz .LBB0_1066
	v_mul_f32_e32 v82, 0xbfb8aa3b, v86
	v_mul_f32_e32 v83, 0xbfb8aa3b, v87
	v_exp_f32_e32 v82, v82
	v_exp_f32_e32 v83, v83
	v_mul_f32_e32 v84, 0xbfb8aa3b, v88
	v_mul_f32_e32 v85, 0xbfb8aa3b, v89
	v_exp_f32_e32 v84, v84
	v_pk_add_f32 v[82:83], v[82:83], 1.0 op_sel_hi:[1,0]
	v_exp_f32_e32 v85, v85
	v_rcp_f32_e32 v97, v83
	v_pk_add_f32 v[84:85], v[84:85], 1.0 op_sel_hi:[1,0]
	v_mul_f32_e32 v83, v87, v97
	v_rcp_f32_e32 v97, v82
	s_nop 0
	v_mul_f32_e32 v82, v86, v97
	v_rcp_f32_e32 v97, v85
	v_pk_mul_f32 v[82:83], v[92:93], v[82:83]
	v_mul_f32_e32 v85, v89, v97
	v_rcp_f32_e32 v97, v84
	s_mov_b64 s[2:3], 0
	v_mul_f32_e32 v84, v88, v97
	v_pk_mul_f32 v[84:85], v[90:91], v[84:85]
.LBB0_1066:
	s_andn2_b64 vcc, exec, s[2:3]
	s_cbranch_vccnz .LBB0_1068
	v_mul_f32_e32 v82, 0xbfb8aa3b, v92
	v_mul_f32_e32 v83, 0xbfb8aa3b, v93
	v_exp_f32_e32 v82, v82
	v_exp_f32_e32 v83, v83
	v_mul_f32_e32 v84, 0xbfb8aa3b, v90
	v_mul_f32_e32 v85, 0xbfb8aa3b, v91
	v_exp_f32_e32 v84, v84
	v_pk_add_f32 v[82:83], v[82:83], 1.0 op_sel_hi:[1,0]
	v_exp_f32_e32 v85, v85
	v_rcp_f32_e32 v91, v83
	v_pk_add_f32 v[84:85], v[84:85], 1.0 op_sel_hi:[1,0]
	v_mov_b32_e32 v83, v91
	v_rcp_f32_e32 v91, v82
	s_nop 0
	v_mov_b32_e32 v82, v91
	v_rcp_f32_e32 v91, v85
	v_pk_mul_f32 v[82:83], v[86:87], v[82:83]
	v_mov_b32_e32 v85, v91
	v_rcp_f32_e32 v91, v84
	s_nop 0
	v_mov_b32_e32 v84, v91
	v_pk_mul_f32 v[84:85], v[88:89], v[84:85]
.LBB0_1068:
	v_cvt_pk_bf16_f32 v82, v82, v83
	v_cvt_pk_bf16_f32 v83, v84, v85
	global_store_dwordx2 v[94:95], v[82:83], off offset:32
	v_pk_add_f32 v[80:81], v[80:81], v[144:145]
	v_pk_add_f32 v[78:79], v[78:79], v[142:143]
	v_pk_add_f32 v[82:83], v[76:77], v[140:141]
	v_pk_add_f32 v[84:85], v[74:75], v[138:139]
	s_and_b64 vcc, exec, s[4:5]
	s_mov_b64 s[2:3], -1
	s_cbranch_vccnz .LBB0_1070
	v_mul_f32_e32 v74, 0xbfb8aa3b, v78
	v_mul_f32_e32 v75, 0xbfb8aa3b, v79
	v_exp_f32_e32 v74, v74
	v_exp_f32_e32 v75, v75
	v_mul_f32_e32 v76, 0xbfb8aa3b, v80
	v_mul_f32_e32 v77, 0xbfb8aa3b, v81
	v_exp_f32_e32 v76, v76
	v_pk_add_f32 v[74:75], v[74:75], 1.0 op_sel_hi:[1,0]
	v_exp_f32_e32 v77, v77
	v_rcp_f32_e32 v87, v75
	v_pk_add_f32 v[76:77], v[76:77], 1.0 op_sel_hi:[1,0]
	v_mul_f32_e32 v75, v79, v87
	v_rcp_f32_e32 v87, v74
	s_nop 0
	v_mul_f32_e32 v74, v78, v87
	v_rcp_f32_e32 v87, v77
	v_pk_mul_f32 v[74:75], v[84:85], v[74:75]
	v_mul_f32_e32 v77, v81, v87
	v_rcp_f32_e32 v87, v76
	s_mov_b64 s[2:3], 0
	v_mul_f32_e32 v76, v80, v87
	v_pk_mul_f32 v[76:77], v[82:83], v[76:77]
.LBB0_1070:
	s_andn2_b64 vcc, exec, s[2:3]
	s_cbranch_vccnz .LBB0_1072
	v_mul_f32_e32 v74, 0xbfb8aa3b, v84
	v_mul_f32_e32 v75, 0xbfb8aa3b, v85
	v_exp_f32_e32 v74, v74
	v_exp_f32_e32 v75, v75
	v_mul_f32_e32 v76, 0xbfb8aa3b, v82
	v_mul_f32_e32 v77, 0xbfb8aa3b, v83
	v_exp_f32_e32 v76, v76
	v_pk_add_f32 v[74:75], v[74:75], 1.0 op_sel_hi:[1,0]
	v_exp_f32_e32 v77, v77
	v_rcp_f32_e32 v83, v75
	v_pk_add_f32 v[76:77], v[76:77], 1.0 op_sel_hi:[1,0]
	v_mov_b32_e32 v75, v83
	v_rcp_f32_e32 v83, v74
	s_nop 0
	v_mov_b32_e32 v74, v83
	v_rcp_f32_e32 v83, v77
	v_pk_mul_f32 v[74:75], v[78:79], v[74:75]
	v_mov_b32_e32 v77, v83
	v_rcp_f32_e32 v83, v76
	s_nop 0
	v_mov_b32_e32 v76, v83
	v_pk_mul_f32 v[76:77], v[80:81], v[76:77]
.LBB0_1072:
	v_add_u32_e32 v78, 48, v160
	v_mad_i64_i32 v[78:79], s[2:3], v0, v78, 0
	v_lshl_add_u64 v[78:79], v[78:79], 1, v[126:127]
	v_cvt_pk_bf16_f32 v74, v74, v75
	v_cvt_pk_bf16_f32 v75, v76, v77
	global_store_dwordx2 v[78:79], v[74:75], off
	v_pk_add_f32 v[72:73], v[72:73], v[132:133]
	v_pk_add_f32 v[70:71], v[70:71], v[130:131]
	v_pk_add_f32 v[74:75], v[68:69], v[136:137]
	v_pk_add_f32 v[76:77], v[66:67], v[134:135]
	s_and_b64 vcc, exec, s[4:5]
	s_mov_b64 s[2:3], -1
	s_cbranch_vccnz .LBB0_1074
	v_mul_f32_e32 v66, 0xbfb8aa3b, v70
	v_mul_f32_e32 v67, 0xbfb8aa3b, v71
	v_exp_f32_e32 v66, v66
	v_exp_f32_e32 v67, v67
	v_mul_f32_e32 v68, 0xbfb8aa3b, v72
	v_mul_f32_e32 v69, 0xbfb8aa3b, v73
	v_exp_f32_e32 v68, v68
	v_pk_add_f32 v[66:67], v[66:67], 1.0 op_sel_hi:[1,0]
	v_exp_f32_e32 v69, v69
	v_rcp_f32_e32 v81, v67
	v_pk_add_f32 v[68:69], v[68:69], 1.0 op_sel_hi:[1,0]
	v_mul_f32_e32 v67, v71, v81
	v_rcp_f32_e32 v81, v66
	s_nop 0
	v_mul_f32_e32 v66, v70, v81
	v_rcp_f32_e32 v81, v69
	v_pk_mul_f32 v[66:67], v[76:77], v[66:67]
	v_mul_f32_e32 v69, v73, v81
	v_rcp_f32_e32 v81, v68
	s_mov_b64 s[2:3], 0
	v_mul_f32_e32 v68, v72, v81
	v_pk_mul_f32 v[68:69], v[74:75], v[68:69]
.LBB0_1074:
	s_andn2_b64 vcc, exec, s[2:3]
	s_cbranch_vccnz .LBB0_1076
	v_mul_f32_e32 v66, 0xbfb8aa3b, v76
	v_mul_f32_e32 v67, 0xbfb8aa3b, v77
	v_exp_f32_e32 v66, v66
	v_exp_f32_e32 v67, v67
	v_mul_f32_e32 v68, 0xbfb8aa3b, v74
	v_mul_f32_e32 v69, 0xbfb8aa3b, v75
	v_exp_f32_e32 v68, v68
	v_pk_add_f32 v[66:67], v[66:67], 1.0 op_sel_hi:[1,0]
	v_exp_f32_e32 v69, v69
	v_rcp_f32_e32 v75, v67
	v_pk_add_f32 v[68:69], v[68:69], 1.0 op_sel_hi:[1,0]
	v_mov_b32_e32 v67, v75
	v_rcp_f32_e32 v75, v66
	s_nop 0
	v_mov_b32_e32 v66, v75
	v_rcp_f32_e32 v75, v69
	v_pk_mul_f32 v[66:67], v[70:71], v[66:67]
	v_mov_b32_e32 v69, v75
	v_rcp_f32_e32 v75, v68
	s_nop 0
	v_mov_b32_e32 v68, v75
	v_pk_mul_f32 v[68:69], v[72:73], v[68:69]
.LBB0_1076:
	v_cvt_pk_bf16_f32 v66, v66, v67
	v_cvt_pk_bf16_f32 v67, v68, v69
	global_store_dwordx2 v[78:79], v[66:67], off offset:32
	v_pk_add_f32 v[64:65], v[64:65], v[144:145]
	v_pk_add_f32 v[62:63], v[62:63], v[142:143]
	v_pk_add_f32 v[66:67], v[60:61], v[140:141]
	v_pk_add_f32 v[68:69], v[58:59], v[138:139]
	s_and_b64 vcc, exec, s[4:5]
	s_mov_b64 s[2:3], -1
	s_cbranch_vccnz .LBB0_1078
	v_mul_f32_e32 v58, 0xbfb8aa3b, v62
	v_mul_f32_e32 v59, 0xbfb8aa3b, v63
	v_exp_f32_e32 v58, v58
	v_exp_f32_e32 v59, v59
	v_mul_f32_e32 v60, 0xbfb8aa3b, v64
	v_mul_f32_e32 v61, 0xbfb8aa3b, v65
	v_exp_f32_e32 v60, v60
	v_pk_add_f32 v[58:59], v[58:59], 1.0 op_sel_hi:[1,0]
	v_exp_f32_e32 v61, v61
	v_rcp_f32_e32 v71, v59
	v_pk_add_f32 v[60:61], v[60:61], 1.0 op_sel_hi:[1,0]
	v_mul_f32_e32 v59, v63, v71
	v_rcp_f32_e32 v71, v58
	s_nop 0
	v_mul_f32_e32 v58, v62, v71
	v_rcp_f32_e32 v71, v61
	v_pk_mul_f32 v[58:59], v[68:69], v[58:59]
	v_mul_f32_e32 v61, v65, v71
	v_rcp_f32_e32 v71, v60
	s_mov_b64 s[2:3], 0
	v_mul_f32_e32 v60, v64, v71
	v_pk_mul_f32 v[60:61], v[66:67], v[60:61]
.LBB0_1078:
	s_andn2_b64 vcc, exec, s[2:3]
	s_cbranch_vccnz .LBB0_1080
	v_mul_f32_e32 v58, 0xbfb8aa3b, v68
	v_mul_f32_e32 v59, 0xbfb8aa3b, v69
	v_exp_f32_e32 v58, v58
	v_exp_f32_e32 v59, v59
	v_mul_f32_e32 v60, 0xbfb8aa3b, v66
	v_mul_f32_e32 v61, 0xbfb8aa3b, v67
	v_exp_f32_e32 v60, v60
	v_pk_add_f32 v[58:59], v[58:59], 1.0 op_sel_hi:[1,0]
	v_exp_f32_e32 v61, v61
	v_rcp_f32_e32 v67, v59
	v_pk_add_f32 v[60:61], v[60:61], 1.0 op_sel_hi:[1,0]
	v_mov_b32_e32 v59, v67
	v_rcp_f32_e32 v67, v58
	s_nop 0
	v_mov_b32_e32 v58, v67
	v_rcp_f32_e32 v67, v61
	v_pk_mul_f32 v[58:59], v[62:63], v[58:59]
	v_mov_b32_e32 v61, v67
	v_rcp_f32_e32 v67, v60
	s_nop 0
	v_mov_b32_e32 v60, v67
	v_pk_mul_f32 v[60:61], v[64:65], v[60:61]
.LBB0_1080:
	v_add_u32_e32 v62, 0x80, v160
	v_mad_i64_i32 v[62:63], s[2:3], v0, v62, 0
	v_lshl_add_u64 v[62:63], v[62:63], 1, v[126:127]
	v_cvt_pk_bf16_f32 v58, v58, v59
	v_cvt_pk_bf16_f32 v59, v60, v61
	global_store_dwordx2 v[62:63], v[58:59], off
	v_pk_add_f32 v[56:57], v[56:57], v[132:133]
	v_pk_add_f32 v[54:55], v[54:55], v[130:131]
	v_pk_add_f32 v[58:59], v[52:53], v[136:137]
	v_pk_add_f32 v[60:61], v[50:51], v[134:135]
	s_and_b64 vcc, exec, s[4:5]
	s_mov_b64 s[2:3], -1
	s_cbranch_vccnz .LBB0_1082
	v_mul_f32_e32 v50, 0xbfb8aa3b, v54
	v_mul_f32_e32 v51, 0xbfb8aa3b, v55
	v_exp_f32_e32 v50, v50
	v_exp_f32_e32 v51, v51
	v_mul_f32_e32 v52, 0xbfb8aa3b, v56
	v_mul_f32_e32 v53, 0xbfb8aa3b, v57
	v_exp_f32_e32 v52, v52
	v_pk_add_f32 v[50:51], v[50:51], 1.0 op_sel_hi:[1,0]
	v_exp_f32_e32 v53, v53
	v_rcp_f32_e32 v65, v51
	v_pk_add_f32 v[52:53], v[52:53], 1.0 op_sel_hi:[1,0]
	v_mul_f32_e32 v51, v55, v65
	v_rcp_f32_e32 v65, v50
	s_nop 0
	v_mul_f32_e32 v50, v54, v65
	v_rcp_f32_e32 v65, v53
	v_pk_mul_f32 v[50:51], v[60:61], v[50:51]
	v_mul_f32_e32 v53, v57, v65
	v_rcp_f32_e32 v65, v52
	s_mov_b64 s[2:3], 0
	v_mul_f32_e32 v52, v56, v65
	v_pk_mul_f32 v[52:53], v[58:59], v[52:53]
.LBB0_1082:
	s_andn2_b64 vcc, exec, s[2:3]
	s_cbranch_vccnz .LBB0_1084
	v_mul_f32_e32 v50, 0xbfb8aa3b, v60
	v_mul_f32_e32 v51, 0xbfb8aa3b, v61
	v_exp_f32_e32 v50, v50
	v_exp_f32_e32 v51, v51
	v_mul_f32_e32 v52, 0xbfb8aa3b, v58
	v_mul_f32_e32 v53, 0xbfb8aa3b, v59
	v_exp_f32_e32 v52, v52
	v_pk_add_f32 v[50:51], v[50:51], 1.0 op_sel_hi:[1,0]
	v_exp_f32_e32 v53, v53
	v_rcp_f32_e32 v59, v51
	v_pk_add_f32 v[52:53], v[52:53], 1.0 op_sel_hi:[1,0]
	v_mov_b32_e32 v51, v59
	v_rcp_f32_e32 v59, v50
	s_nop 0
	v_mov_b32_e32 v50, v59
	v_rcp_f32_e32 v59, v53
	v_pk_mul_f32 v[50:51], v[54:55], v[50:51]
	v_mov_b32_e32 v53, v59
	v_rcp_f32_e32 v59, v52
	s_nop 0
	v_mov_b32_e32 v52, v59
	v_pk_mul_f32 v[52:53], v[56:57], v[52:53]
.LBB0_1084:
	v_cvt_pk_bf16_f32 v50, v50, v51
	v_cvt_pk_bf16_f32 v51, v52, v53
	global_store_dwordx2 v[62:63], v[50:51], off offset:32
	v_pk_add_f32 v[48:49], v[48:49], v[144:145]
	v_pk_add_f32 v[46:47], v[46:47], v[142:143]
	v_pk_add_f32 v[50:51], v[44:45], v[140:141]
	v_pk_add_f32 v[52:53], v[42:43], v[138:139]
	s_and_b64 vcc, exec, s[4:5]
	s_mov_b64 s[2:3], -1
	s_cbranch_vccnz .LBB0_1086
	v_mul_f32_e32 v42, 0xbfb8aa3b, v46
	v_mul_f32_e32 v43, 0xbfb8aa3b, v47
	v_exp_f32_e32 v42, v42
	v_exp_f32_e32 v43, v43
	v_mul_f32_e32 v44, 0xbfb8aa3b, v48
	v_mul_f32_e32 v45, 0xbfb8aa3b, v49
	v_exp_f32_e32 v44, v44
	v_pk_add_f32 v[42:43], v[42:43], 1.0 op_sel_hi:[1,0]
	v_exp_f32_e32 v45, v45
	v_rcp_f32_e32 v55, v43
	v_pk_add_f32 v[44:45], v[44:45], 1.0 op_sel_hi:[1,0]
	v_mul_f32_e32 v43, v47, v55
	v_rcp_f32_e32 v55, v42
	s_nop 0
	v_mul_f32_e32 v42, v46, v55
	v_rcp_f32_e32 v55, v45
	v_pk_mul_f32 v[42:43], v[52:53], v[42:43]
	v_mul_f32_e32 v45, v49, v55
	v_rcp_f32_e32 v55, v44
	s_mov_b64 s[2:3], 0
	v_mul_f32_e32 v44, v48, v55
	v_pk_mul_f32 v[44:45], v[50:51], v[44:45]
.LBB0_1086:
	s_andn2_b64 vcc, exec, s[2:3]
	s_cbranch_vccnz .LBB0_1088
	v_mul_f32_e32 v42, 0xbfb8aa3b, v52
	v_mul_f32_e32 v43, 0xbfb8aa3b, v53
	v_exp_f32_e32 v42, v42
	v_exp_f32_e32 v43, v43
	v_mul_f32_e32 v44, 0xbfb8aa3b, v50
	v_mul_f32_e32 v45, 0xbfb8aa3b, v51
	v_exp_f32_e32 v44, v44
	v_pk_add_f32 v[42:43], v[42:43], 1.0 op_sel_hi:[1,0]
	v_exp_f32_e32 v45, v45
	v_rcp_f32_e32 v51, v43
	v_pk_add_f32 v[44:45], v[44:45], 1.0 op_sel_hi:[1,0]
	v_mov_b32_e32 v43, v51
	v_rcp_f32_e32 v51, v42
	s_nop 0
	v_mov_b32_e32 v42, v51
	v_rcp_f32_e32 v51, v45
	v_pk_mul_f32 v[42:43], v[46:47], v[42:43]
	v_mov_b32_e32 v45, v51
	v_rcp_f32_e32 v51, v44
	s_nop 0
	v_mov_b32_e32 v44, v51
	v_pk_mul_f32 v[44:45], v[48:49], v[44:45]
.LBB0_1088:
	v_add_u32_e32 v46, 0x90, v160
	v_mad_i64_i32 v[46:47], s[2:3], v0, v46, 0
	v_lshl_add_u64 v[46:47], v[46:47], 1, v[126:127]
	v_cvt_pk_bf16_f32 v42, v42, v43
	v_cvt_pk_bf16_f32 v43, v44, v45
	global_store_dwordx2 v[46:47], v[42:43], off
	v_pk_add_f32 v[40:41], v[40:41], v[132:133]
	v_pk_add_f32 v[38:39], v[38:39], v[130:131]
	v_pk_add_f32 v[42:43], v[36:37], v[136:137]
	v_pk_add_f32 v[44:45], v[34:35], v[134:135]
	s_and_b64 vcc, exec, s[4:5]
	s_mov_b64 s[2:3], -1
	s_cbranch_vccnz .LBB0_1090
	v_mul_f32_e32 v34, 0xbfb8aa3b, v38
	v_mul_f32_e32 v35, 0xbfb8aa3b, v39
	v_exp_f32_e32 v34, v34
	v_exp_f32_e32 v35, v35
	v_mul_f32_e32 v36, 0xbfb8aa3b, v40
	v_mul_f32_e32 v37, 0xbfb8aa3b, v41
	v_exp_f32_e32 v36, v36
	v_pk_add_f32 v[34:35], v[34:35], 1.0 op_sel_hi:[1,0]
	v_exp_f32_e32 v37, v37
	v_rcp_f32_e32 v49, v35
	v_pk_add_f32 v[36:37], v[36:37], 1.0 op_sel_hi:[1,0]
	v_mul_f32_e32 v35, v39, v49
	v_rcp_f32_e32 v49, v34
	s_nop 0
	v_mul_f32_e32 v34, v38, v49
	v_rcp_f32_e32 v49, v37
	v_pk_mul_f32 v[34:35], v[44:45], v[34:35]
	v_mul_f32_e32 v37, v41, v49
	v_rcp_f32_e32 v49, v36
	s_mov_b64 s[2:3], 0
	v_mul_f32_e32 v36, v40, v49
	v_pk_mul_f32 v[36:37], v[42:43], v[36:37]
.LBB0_1090:
	s_andn2_b64 vcc, exec, s[2:3]
	s_cbranch_vccnz .LBB0_1092
	v_mul_f32_e32 v34, 0xbfb8aa3b, v44
	v_mul_f32_e32 v35, 0xbfb8aa3b, v45
	v_exp_f32_e32 v34, v34
	v_exp_f32_e32 v35, v35
	v_mul_f32_e32 v36, 0xbfb8aa3b, v42
	v_mul_f32_e32 v37, 0xbfb8aa3b, v43
	v_exp_f32_e32 v36, v36
	v_pk_add_f32 v[34:35], v[34:35], 1.0 op_sel_hi:[1,0]
	v_exp_f32_e32 v37, v37
	v_rcp_f32_e32 v43, v35
	v_pk_add_f32 v[36:37], v[36:37], 1.0 op_sel_hi:[1,0]
	v_mov_b32_e32 v35, v43
	v_rcp_f32_e32 v43, v34
	s_nop 0
	v_mov_b32_e32 v34, v43
	v_rcp_f32_e32 v43, v37
	v_pk_mul_f32 v[34:35], v[38:39], v[34:35]
	v_mov_b32_e32 v37, v43
	v_rcp_f32_e32 v43, v36
	s_nop 0
	v_mov_b32_e32 v36, v43
	v_pk_mul_f32 v[36:37], v[40:41], v[36:37]
.LBB0_1092:
	v_cvt_pk_bf16_f32 v34, v34, v35
	v_cvt_pk_bf16_f32 v35, v36, v37
	global_store_dwordx2 v[46:47], v[34:35], off offset:32
	v_pk_add_f32 v[32:33], v[32:33], v[144:145]
	v_pk_add_f32 v[30:31], v[30:31], v[142:143]
	v_pk_add_f32 v[34:35], v[28:29], v[140:141]
	v_pk_add_f32 v[36:37], v[26:27], v[138:139]
	s_and_b64 vcc, exec, s[4:5]
	s_mov_b64 s[2:3], -1
	s_cbranch_vccnz .LBB0_1094
	v_mul_f32_e32 v26, 0xbfb8aa3b, v30
	v_mul_f32_e32 v27, 0xbfb8aa3b, v31
	v_exp_f32_e32 v26, v26
	v_exp_f32_e32 v27, v27
	v_mul_f32_e32 v28, 0xbfb8aa3b, v32
	v_mul_f32_e32 v29, 0xbfb8aa3b, v33
	v_exp_f32_e32 v28, v28
	v_pk_add_f32 v[26:27], v[26:27], 1.0 op_sel_hi:[1,0]
	v_exp_f32_e32 v29, v29
	v_rcp_f32_e32 v39, v27
	v_pk_add_f32 v[28:29], v[28:29], 1.0 op_sel_hi:[1,0]
	v_mul_f32_e32 v27, v31, v39
	v_rcp_f32_e32 v39, v26
	s_nop 0
	v_mul_f32_e32 v26, v30, v39
	v_rcp_f32_e32 v39, v29
	v_pk_mul_f32 v[26:27], v[36:37], v[26:27]
	v_mul_f32_e32 v29, v33, v39
	v_rcp_f32_e32 v39, v28
	s_mov_b64 s[2:3], 0
	v_mul_f32_e32 v28, v32, v39
	v_pk_mul_f32 v[28:29], v[34:35], v[28:29]
.LBB0_1094:
	s_andn2_b64 vcc, exec, s[2:3]
	s_cbranch_vccnz .LBB0_1096
	v_mul_f32_e32 v26, 0xbfb8aa3b, v36
	v_mul_f32_e32 v27, 0xbfb8aa3b, v37
	v_exp_f32_e32 v26, v26
	v_exp_f32_e32 v27, v27
	v_mul_f32_e32 v28, 0xbfb8aa3b, v34
	v_mul_f32_e32 v29, 0xbfb8aa3b, v35
	v_exp_f32_e32 v28, v28
	v_pk_add_f32 v[26:27], v[26:27], 1.0 op_sel_hi:[1,0]
	v_exp_f32_e32 v29, v29
	v_rcp_f32_e32 v35, v27
	v_pk_add_f32 v[28:29], v[28:29], 1.0 op_sel_hi:[1,0]
	v_mov_b32_e32 v27, v35
	v_rcp_f32_e32 v35, v26
	s_nop 0
	v_mov_b32_e32 v26, v35
	v_rcp_f32_e32 v35, v29
	v_pk_mul_f32 v[26:27], v[30:31], v[26:27]
	v_mov_b32_e32 v29, v35
	v_rcp_f32_e32 v35, v28
	s_nop 0
	v_mov_b32_e32 v28, v35
	v_pk_mul_f32 v[28:29], v[32:33], v[28:29]
.LBB0_1096:
	v_add_u32_e32 v30, 0xa0, v160
	v_mad_i64_i32 v[30:31], s[2:3], v0, v30, 0
	v_lshl_add_u64 v[30:31], v[30:31], 1, v[126:127]
	v_cvt_pk_bf16_f32 v26, v26, v27
	v_cvt_pk_bf16_f32 v27, v28, v29
	global_store_dwordx2 v[30:31], v[26:27], off
	v_pk_add_f32 v[24:25], v[24:25], v[132:133]
	v_pk_add_f32 v[22:23], v[22:23], v[130:131]
	v_pk_add_f32 v[26:27], v[20:21], v[136:137]
	v_pk_add_f32 v[28:29], v[18:19], v[134:135]
	s_and_b64 vcc, exec, s[4:5]
	s_mov_b64 s[2:3], -1
	s_cbranch_vccnz .LBB0_1098
	v_mul_f32_e32 v18, 0xbfb8aa3b, v22
	v_mul_f32_e32 v19, 0xbfb8aa3b, v23
	v_exp_f32_e32 v18, v18
	v_exp_f32_e32 v19, v19
	v_mul_f32_e32 v20, 0xbfb8aa3b, v24
	v_mul_f32_e32 v21, 0xbfb8aa3b, v25
	v_exp_f32_e32 v20, v20
	v_pk_add_f32 v[18:19], v[18:19], 1.0 op_sel_hi:[1,0]
	v_exp_f32_e32 v21, v21
	v_rcp_f32_e32 v33, v19
	v_pk_add_f32 v[20:21], v[20:21], 1.0 op_sel_hi:[1,0]
	v_mul_f32_e32 v19, v23, v33
	v_rcp_f32_e32 v33, v18
	s_nop 0
	v_mul_f32_e32 v18, v22, v33
	v_rcp_f32_e32 v33, v21
	v_pk_mul_f32 v[18:19], v[28:29], v[18:19]
	v_mul_f32_e32 v21, v25, v33
	v_rcp_f32_e32 v33, v20
	s_mov_b64 s[2:3], 0
	v_mul_f32_e32 v20, v24, v33
	v_pk_mul_f32 v[20:21], v[26:27], v[20:21]
.LBB0_1098:
	s_andn2_b64 vcc, exec, s[2:3]
	s_cbranch_vccnz .LBB0_1100
	v_mul_f32_e32 v18, 0xbfb8aa3b, v28
	v_mul_f32_e32 v19, 0xbfb8aa3b, v29
	v_exp_f32_e32 v18, v18
	v_exp_f32_e32 v19, v19
	v_mul_f32_e32 v20, 0xbfb8aa3b, v26
	v_mul_f32_e32 v21, 0xbfb8aa3b, v27
	v_exp_f32_e32 v20, v20
	v_pk_add_f32 v[18:19], v[18:19], 1.0 op_sel_hi:[1,0]
	v_exp_f32_e32 v21, v21
	v_rcp_f32_e32 v27, v19
	v_pk_add_f32 v[20:21], v[20:21], 1.0 op_sel_hi:[1,0]
	v_mov_b32_e32 v19, v27
	v_rcp_f32_e32 v27, v18
	s_nop 0
	v_mov_b32_e32 v18, v27
	v_rcp_f32_e32 v27, v21
	v_pk_mul_f32 v[18:19], v[22:23], v[18:19]
	v_mov_b32_e32 v21, v27
	v_rcp_f32_e32 v27, v20
	s_nop 0
	v_mov_b32_e32 v20, v27
	v_pk_mul_f32 v[20:21], v[24:25], v[20:21]
.LBB0_1100:
	v_cvt_pk_bf16_f32 v18, v18, v19
	v_cvt_pk_bf16_f32 v19, v20, v21
	global_store_dwordx2 v[30:31], v[18:19], off offset:32
	v_pk_add_f32 v[16:17], v[16:17], v[144:145]
	v_pk_add_f32 v[14:15], v[14:15], v[142:143]
	v_pk_add_f32 v[18:19], v[12:13], v[140:141]
	v_pk_add_f32 v[20:21], v[10:11], v[138:139]
	s_and_b64 vcc, exec, s[4:5]
	s_mov_b64 s[2:3], -1
	s_cbranch_vccnz .LBB0_1102
	v_mul_f32_e32 v10, 0xbfb8aa3b, v14
	v_mul_f32_e32 v11, 0xbfb8aa3b, v15
	v_exp_f32_e32 v10, v10
	v_exp_f32_e32 v11, v11
	v_mul_f32_e32 v12, 0xbfb8aa3b, v16
	v_mul_f32_e32 v13, 0xbfb8aa3b, v17
	v_exp_f32_e32 v12, v12
	v_pk_add_f32 v[10:11], v[10:11], 1.0 op_sel_hi:[1,0]
	v_exp_f32_e32 v13, v13
	v_rcp_f32_e32 v23, v11
	v_pk_add_f32 v[12:13], v[12:13], 1.0 op_sel_hi:[1,0]
	v_mul_f32_e32 v11, v15, v23
	v_rcp_f32_e32 v23, v10
	s_nop 0
	v_mul_f32_e32 v10, v14, v23
	v_rcp_f32_e32 v23, v13
	v_pk_mul_f32 v[10:11], v[20:21], v[10:11]
	v_mul_f32_e32 v13, v17, v23
	v_rcp_f32_e32 v23, v12
	s_mov_b64 s[2:3], 0
	v_mul_f32_e32 v12, v16, v23
	v_pk_mul_f32 v[12:13], v[18:19], v[12:13]
.LBB0_1102:
	s_andn2_b64 vcc, exec, s[2:3]
	s_cbranch_vccnz .LBB0_1104
	v_mul_f32_e32 v10, 0xbfb8aa3b, v20
	v_mul_f32_e32 v11, 0xbfb8aa3b, v21
	v_exp_f32_e32 v10, v10
	v_exp_f32_e32 v11, v11
	v_mul_f32_e32 v12, 0xbfb8aa3b, v18
	v_mul_f32_e32 v13, 0xbfb8aa3b, v19
	v_exp_f32_e32 v12, v12
	v_pk_add_f32 v[10:11], v[10:11], 1.0 op_sel_hi:[1,0]
	v_exp_f32_e32 v13, v13
	v_rcp_f32_e32 v19, v11
	v_pk_add_f32 v[12:13], v[12:13], 1.0 op_sel_hi:[1,0]
	v_mov_b32_e32 v11, v19
	v_rcp_f32_e32 v19, v10
	s_nop 0
	v_mov_b32_e32 v10, v19
	v_rcp_f32_e32 v19, v13
	v_pk_mul_f32 v[10:11], v[14:15], v[10:11]
	v_mov_b32_e32 v13, v19
	v_rcp_f32_e32 v19, v12
	s_nop 0
	v_mov_b32_e32 v12, v19
	v_pk_mul_f32 v[12:13], v[16:17], v[12:13]
.LBB0_1104:
	v_add_u32_e32 v14, 0xb0, v160
	v_mad_i64_i32 v[14:15], s[2:3], v0, v14, 0
	v_lshl_add_u64 v[14:15], v[14:15], 1, v[126:127]
	v_cvt_pk_bf16_f32 v10, v10, v11
	v_cvt_pk_bf16_f32 v11, v12, v13
	global_store_dwordx2 v[14:15], v[10:11], off
	v_pk_add_f32 v[8:9], v[8:9], v[132:133]
	v_pk_add_f32 v[6:7], v[6:7], v[130:131]
	v_pk_add_f32 v[10:11], v[4:5], v[136:137]
	v_pk_add_f32 v[12:13], v[2:3], v[134:135]
	s_and_b64 vcc, exec, s[4:5]
	s_mov_b64 s[2:3], -1
	s_cbranch_vccnz .LBB0_1106
	v_mul_f32_e32 v0, 0xbfb8aa3b, v6
	v_exp_f32_e32 v2, v0
	v_mul_f32_e32 v0, 0xbfb8aa3b, v7
	v_exp_f32_e32 v3, v0
	v_mul_f32_e32 v0, 0xbfb8aa3b, v8
	v_exp_f32_e32 v4, v0
	v_mul_f32_e32 v0, 0xbfb8aa3b, v9
	v_pk_add_f32 v[2:3], v[2:3], 1.0 op_sel_hi:[1,0]
	v_exp_f32_e32 v5, v0
	v_rcp_f32_e32 v16, v3
	v_pk_add_f32 v[4:5], v[4:5], 1.0 op_sel_hi:[1,0]
	v_mul_f32_e32 v3, v7, v16
	v_rcp_f32_e32 v16, v2
	s_nop 0
	v_mul_f32_e32 v2, v6, v16
	v_rcp_f32_e32 v16, v5
	v_pk_mul_f32 v[2:3], v[12:13], v[2:3]
	v_mul_f32_e32 v5, v9, v16
	v_rcp_f32_e32 v16, v4
	s_mov_b64 s[2:3], 0
	v_mul_f32_e32 v4, v8, v16
	v_pk_mul_f32 v[4:5], v[10:11], v[4:5]
.LBB0_1106:
	s_andn2_b64 vcc, exec, s[2:3]
	s_cbranch_vccnz .LBB0_1108
	v_mul_f32_e32 v0, 0xbfb8aa3b, v12
	v_exp_f32_e32 v2, v0
	v_mul_f32_e32 v0, 0xbfb8aa3b, v13
	v_exp_f32_e32 v3, v0
	v_mul_f32_e32 v0, 0xbfb8aa3b, v10
	v_exp_f32_e32 v4, v0
	v_mul_f32_e32 v0, 0xbfb8aa3b, v11
	v_pk_add_f32 v[2:3], v[2:3], 1.0 op_sel_hi:[1,0]
	v_exp_f32_e32 v5, v0
	v_rcp_f32_e32 v10, v3
	v_pk_add_f32 v[4:5], v[4:5], 1.0 op_sel_hi:[1,0]
	v_mov_b32_e32 v3, v10
	v_rcp_f32_e32 v10, v2
	s_nop 0
	v_mov_b32_e32 v2, v10
	v_rcp_f32_e32 v10, v5
	v_pk_mul_f32 v[2:3], v[6:7], v[2:3]
	v_mov_b32_e32 v5, v10
	v_rcp_f32_e32 v10, v4
	s_nop 0
	v_mov_b32_e32 v4, v10
	v_pk_mul_f32 v[4:5], v[8:9], v[4:5]
